# GEMM K-loop: an extra s_setprio 0 / s_setprio 1 yield point after every 8 MFMAs of each 16-MFMA run (twice as many arbitration points for the loading wave half)
# speedup vs baseline: 1.0064x; 1.0064x over previous
; #define PG8_STAGE(bufoff, gbase, voff) do { _Pragma("unroll") for (int _i = 0; _i < 2; ++_i) \
;         __builtin_amdgcn_global_load_lds((const unsigned*)((const char*)(gbase) + (voff)[_i]), (LAS unsigned*)(lds + (bufoff) + ldsw + _i * 8192), 16, 0, 0); } while (0)
; #define PG8_LDA(dst, b, h) do { _Pragma("unroll") for (int m = 0; m < 4; ++m) _Pragma("unroll") for (int k = 0; k < 2; ++k) dst[m][k] = *(const LAS bf16x8*)(lds + PG8_SA(b, h) + aoff + m * 2048 + k * 1024); } while (0)
; #define PG8_LDB(dst, b, h) do { _Pragma("unroll") for (int n = 0; n < 2; ++n) _Pragma("unroll") for (int k = 0; k < 2; ++k) dst[n][k] = *(const LAS bf16x8*)(lds + PG8_SB(b, h) + boff + n * 2048 + k * 1024); } while (0)
; #define PG8_MMA(ai, bj, At, Bt) do { __builtin_amdgcn_s_setprio(1); _Pragma("unroll") for (int m = 0; m < 4; ++m) _Pragma("unroll") for (int n = 0; n < 2; ++n) _Pragma("unroll") for (int k = 0; k < 2; ++k) \
;         acc[ai][bj][m][n] = __builtin_amdgcn_mfma_f32_16x16x32_bf16(Bt[n][k], At[m][k], acc[ai][bj][m][n], 0, 0, 0); __builtin_amdgcn_s_setprio(0); } while (0)
; #define PG8_WAIT_V(n) asm volatile("s_waitcnt vmcnt(" #n ")" ::: "memory")
; #define PG8_WAIT_L(n) asm volatile("s_waitcnt lgkmcnt(" #n ")" ::: "memory")
; #define PG8_BAR __builtin_amdgcn_s_barrier()
; #define PG8_SCHED __builtin_amdgcn_sched_barrier(0)
; __device__ __forceinline__ void gemm_phase(LAS unsigned char* lds, const GemmP g, const EpiP e) {
;     ...
;         for (int t = 0; t < nt; t += 2) {
;             const bool last = (t == nt - 2);
;             const char* a1 = cA + (size_t)(t + 1) * kstepA;
;             const char* a2 = last ? nA : cA + (size_t)(t + 2) * kstepA; const char* b2 = last ? nB : cB + (size_t)(t + 2) * kstepB;
;             const char* a3 = a2 + kstepA; const char* b3 = b2 + kstepB;
;             PG8_LDB(B0, 0, 0); PG8_LDB(B1, 0, 1); PG8_SCHED; PG8_LDA(At, 0, 0); PG8_STAGE(PG8_SA(1, 1), a1 + hstepA, voffA);
;             PG8_WAIT_V(8); PG8_WAIT_L(0); PG8_BAR; PG8_MMA(0, 0, At, B0); PG8_MMA(0, 1, At, B1); PG8_BAR; PG8_SCHED;
;             PG8_LDA(At, 0, 1); PG8_STAGE(PG8_SB(0, 0), b2, voffB); PG8_STAGE(PG8_SB(0, 1), b2 + hstepB, voffB); PG8_STAGE(PG8_SA(0, 0), a2, voffA);
;             PG8_WAIT_V(8); PG8_WAIT_L(0); PG8_BAR; PG8_MMA(1, 0, At, B0); PG8_MMA(1, 1, At, B1); PG8_BAR; PG8_SCHED;
.LBB0_392:
	s_cmp_lt_i32 s69, 1
	s_cbranch_scc1 .LBB0_395
	s_add_u32 s24, s78, s90
	s_addc_u32 s25, s79, s7
	s_add_i32 s26, s69, -2
	s_add_u32 s27, s40, 0x100
	s_addc_u32 s28, s41, 0
	s_mov_b64 s[18:19], 0
	s_cmp_eq_u32 s99, 0
	s_cbranch_scc1 .LBB0_394
	s_mov_b32 s99, 0
	s_add_u32 s30, s18, 1
	s_addc_u32 s31, s19, 0
	s_add_u32 s16, s18, 2
	s_addc_u32 s17, s19, 0
	s_lshl_b64 s[20:21], s[16:17], s77
	s_add_u32 s19, s78, s20
	s_addc_u32 s20, s79, s21
	s_cmp_eq_u32 s26, s18
	s_cselect_b32 s21, s51, s20
	s_cselect_b32 s20, s50, s19
	s_cselect_b32 s22, s80, s27
	s_cselect_b32 s23, s81, s28
	s_add_u32 s18, s20, s38
	s_addc_u32 s19, s21, s39
	s_add_i32 s29, 0, 0x10000
	v_add_u32_e32 v96, s29, v179
	s_add_i32 s34, 0, 0x14000
	ds_read_b128 v[132:135], v96
	ds_read_b128 v[136:139], v96 offset:1024
	ds_read_b128 v[160:163], v96 offset:2048
	ds_read_b128 v[164:167], v96 offset:3072
	v_add_u32_e32 v96, s34, v179
	ds_read_b128 v[168:171], v96
	ds_read_b128 v[172:175], v96 offset:1024
	ds_read_b128 v[216:219], v96 offset:2048
	ds_read_b128 v[220:223], v96 offset:3072
	s_lshl_b64 s[30:31], s[30:31], s77
	s_add_u32 s30, s24, s30
	s_addc_u32 s31, s25, s31
	v_lshl_add_u64 v[98:99], s[30:31], 0, v[140:141]
	s_add_i32 m0, s92, 0xc000
	ds_read_b128 v[224:227], v188
	ds_read_b128 v[228:231], v188 offset:1024
	ds_read_b128 v[232:235], v188 offset:2048
	ds_read_b128 v[236:239], v188 offset:3072
	ds_read_b128 v[240:243], v188 offset:4096
	ds_read_b128 v[244:247], v188 offset:5120
	ds_read_b128 v[248:251], v188 offset:6144
	ds_read_b128 v[204:207], v188 offset:7168
	global_load_lds_dwordx4 v[98:99], off
	v_lshl_add_u64 v[98:99], s[30:31], 0, v[142:143]
	s_add_i32 m0, s92, 0xe000
	s_nop 0
	global_load_lds_dwordx4 v[98:99], off
	s_waitcnt vmcnt(24)
	s_waitcnt lgkmcnt(0)
	s_barrier
	s_setprio 1
	s_waitcnt lgkmcnt(0)
	v_mfma_f32_16x16x32_bf16 v[128:131], v[132:135], v[224:227], v[128:131]
	v_mfma_f32_16x16x32_bf16 v[124:127], v[160:163], v[224:227], v[124:127]
	v_mfma_f32_16x16x32_bf16 v[120:123], v[132:135], v[232:235], v[120:123]
	v_mfma_f32_16x16x32_bf16 v[116:119], v[160:163], v[232:235], v[116:119]
	v_mfma_f32_16x16x32_bf16 v[112:115], v[132:135], v[240:243], v[112:115]
	v_mfma_f32_16x16x32_bf16 v[108:111], v[160:163], v[240:243], v[108:111]
	v_mfma_f32_16x16x32_bf16 v[104:107], v[132:135], v[248:251], v[104:107]
	v_mfma_f32_16x16x32_bf16 v[98:101], v[160:163], v[248:251], v[100:103]
	s_setprio 0
	s_setprio 1
	v_mfma_f32_16x16x32_bf16 v[128:131], v[136:139], v[228:231], v[128:131]
	v_mfma_f32_16x16x32_bf16 v[124:127], v[164:167], v[228:231], v[124:127]
	v_mfma_f32_16x16x32_bf16 v[120:123], v[136:139], v[236:239], v[120:123]
	v_mfma_f32_16x16x32_bf16 v[116:119], v[164:167], v[236:239], v[116:119]
	v_mfma_f32_16x16x32_bf16 v[112:115], v[136:139], v[244:247], v[112:115]
	v_mfma_f32_16x16x32_bf16 v[108:111], v[164:167], v[244:247], v[108:111]
	v_mfma_f32_16x16x32_bf16 v[104:107], v[136:139], v[204:207], v[104:107]
	v_mfma_f32_16x16x32_bf16 v[98:101], v[164:167], v[204:207], v[98:101]
	s_setprio 0
	s_setprio 1
	v_mfma_f32_16x16x32_bf16 v[92:95], v[168:171], v[224:227], v[92:95]
	v_mfma_f32_16x16x32_bf16 v[88:91], v[216:219], v[224:227], v[88:91]
	v_mfma_f32_16x16x32_bf16 v[84:87], v[168:171], v[232:235], v[84:87]
	v_mfma_f32_16x16x32_bf16 v[80:83], v[216:219], v[232:235], v[80:83]
	v_mfma_f32_16x16x32_bf16 v[76:79], v[168:171], v[240:243], v[76:79]
	v_mfma_f32_16x16x32_bf16 v[72:75], v[216:219], v[240:243], v[72:75]
	v_mfma_f32_16x16x32_bf16 v[68:71], v[168:171], v[248:251], v[68:71]
	v_mfma_f32_16x16x32_bf16 v[64:67], v[216:219], v[248:251], v[64:67]
	s_setprio 0
	s_setprio 1
	v_mfma_f32_16x16x32_bf16 v[92:95], v[172:175], v[228:231], v[92:95]
	v_mfma_f32_16x16x32_bf16 v[88:91], v[220:223], v[228:231], v[88:91]
	v_mfma_f32_16x16x32_bf16 v[84:87], v[172:175], v[236:239], v[84:87]
	v_mfma_f32_16x16x32_bf16 v[80:83], v[220:223], v[236:239], v[80:83]
	v_mfma_f32_16x16x32_bf16 v[76:79], v[172:175], v[244:247], v[76:79]
	v_mfma_f32_16x16x32_bf16 v[72:75], v[220:223], v[244:247], v[72:75]
	v_mfma_f32_16x16x32_bf16 v[68:71], v[172:175], v[204:207], v[68:71]
	v_mfma_f32_16x16x32_bf16 v[64:67], v[220:223], v[204:207], v[64:67]
	s_setprio 0
	s_barrier
	s_add_i32 s29, s29, s91
	v_lshl_add_u64 v[176:177], s[22:23], 0, v[146:147]
	s_mov_b32 m0, s29
	ds_read_b128 v[204:207], v188 offset:16384
	ds_read_b128 v[224:227], v188 offset:17408
	ds_read_b128 v[228:231], v188 offset:18432
	ds_read_b128 v[232:235], v188 offset:19456
	ds_read_b128 v[236:239], v188 offset:20480
	ds_read_b128 v[240:243], v188 offset:21504
	ds_read_b128 v[244:247], v188 offset:22528
	ds_read_b128 v[248:251], v188 offset:23552
	global_load_lds_dwordx4 v[176:177], off
	s_add_i32 m0, s29, 0x2000
	v_lshl_add_u64 v[210:211], s[22:23], 0, v[144:145]
	s_add_u32 s22, s22, s48
	s_addc_u32 s23, s23, s49
	s_add_i32 s29, s34, s91
	global_load_lds_dwordx4 v[210:211], off
	v_lshl_add_u64 v[212:213], s[22:23], 0, v[146:147]
	s_mov_b32 m0, s29
	v_lshl_add_u64 v[190:191], s[22:23], 0, v[144:145]
	global_load_lds_dwordx4 v[212:213], off
	s_add_i32 m0, s29, 0x2000
	v_lshl_add_u64 v[102:103], s[20:21], 0, v[140:141]
	global_load_lds_dwordx4 v[190:191], off
	s_mov_b32 m0, s92
	s_nop 0
	global_load_lds_dwordx4 v[102:103], off
	v_lshl_add_u64 v[102:103], s[20:21], 0, v[142:143]
	s_mov_b32 m0, s93
	s_nop 0
	global_load_lds_dwordx4 v[102:103], off
	s_waitcnt vmcnt(24)
	s_waitcnt lgkmcnt(0)
	s_barrier
; #define PG8_STAGE(bufoff, gbase, voff) do { _Pragma("unroll") for (int _i = 0; _i < 2; ++_i) \
;         __builtin_amdgcn_global_load_lds((const unsigned*)((const char*)(gbase) + (voff)[_i]), (LAS unsigned*)(lds + (bufoff) + ldsw + _i * 8192), 16, 0, 0); } while (0)
; #define PG8_LDA(dst, b, h) do { _Pragma("unroll") for (int m = 0; m < 4; ++m) _Pragma("unroll") for (int k = 0; k < 2; ++k) dst[m][k] = *(const LAS bf16x8*)(lds + PG8_SA(b, h) + aoff + m * 2048 + k * 1024); } while (0)
; #define PG8_LDB(dst, b, h) do { _Pragma("unroll") for (int n = 0; n < 2; ++n) _Pragma("unroll") for (int k = 0; k < 2; ++k) dst[n][k] = *(const LAS bf16x8*)(lds + PG8_SB(b, h) + boff + n * 2048 + k * 1024); } while (0)
; #define PG8_MMA(ai, bj, At, Bt) do { __builtin_amdgcn_s_setprio(1); _Pragma("unroll") for (int m = 0; m < 4; ++m) _Pragma("unroll") for (int n = 0; n < 2; ++n) _Pragma("unroll") for (int k = 0; k < 2; ++k) \
;         acc[ai][bj][m][n] = __builtin_amdgcn_mfma_f32_16x16x32_bf16(Bt[n][k], At[m][k], acc[ai][bj][m][n], 0, 0, 0); __builtin_amdgcn_s_setprio(0); } while (0)
; #define PG8_WAIT_V(n) asm volatile("s_waitcnt vmcnt(" #n ")" ::: "memory")
; #define PG8_WAIT_L(n) asm volatile("s_waitcnt lgkmcnt(" #n ")" ::: "memory")
; #define PG8_BAR __builtin_amdgcn_s_barrier()
; #define PG8_SCHED __builtin_amdgcn_sched_barrier(0)
; __device__ __forceinline__ void gemm_phase(LAS unsigned char* lds, const GemmP g, const EpiP e) {
;     ...
;             PG8_WAIT_V(8); PG8_WAIT_L(0); PG8_BAR; PG8_MMA(1, 0, At, B0); PG8_MMA(1, 1, At, B1); PG8_BAR; PG8_SCHED;
;             PG8_LDB(B0, 1, 0); PG8_LDB(B1, 1, 1); PG8_SCHED; PG8_LDA(At, 1, 0); PG8_STAGE(PG8_SA(0, 1), a2 + hstepA, voffA);
;             PG8_WAIT_V(8); PG8_WAIT_L(0); PG8_BAR; PG8_MMA(0, 0, At, B0); PG8_MMA(0, 1, At, B1); PG8_BAR; PG8_SCHED;
;             PG8_LDA(At, 1, 1); PG8_STAGE(PG8_SB(1, 0), b3, voffB); PG8_STAGE(PG8_SB(1, 1), b3 + hstepB, voffB); PG8_STAGE(PG8_SA(1, 0), a3, voffA);
	s_setprio 1
	s_waitcnt lgkmcnt(0)
	v_mfma_f32_16x16x32_bf16 v[60:63], v[132:135], v[204:207], v[60:63]
	v_mfma_f32_16x16x32_bf16 v[56:59], v[160:163], v[204:207], v[56:59]
	v_mfma_f32_16x16x32_bf16 v[52:55], v[132:135], v[228:231], v[52:55]
	v_mfma_f32_16x16x32_bf16 v[48:51], v[160:163], v[228:231], v[48:51]
	v_mfma_f32_16x16x32_bf16 v[44:47], v[132:135], v[236:239], v[44:47]
	v_mfma_f32_16x16x32_bf16 v[40:43], v[160:163], v[236:239], v[40:43]
	v_mfma_f32_16x16x32_bf16 v[36:39], v[132:135], v[244:247], v[36:39]
	v_mfma_f32_16x16x32_bf16 v[32:35], v[160:163], v[244:247], v[32:35]
	s_setprio 0
	s_setprio 1
	v_mfma_f32_16x16x32_bf16 v[60:63], v[136:139], v[224:227], v[60:63]
	v_mfma_f32_16x16x32_bf16 v[56:59], v[164:167], v[224:227], v[56:59]
	v_mfma_f32_16x16x32_bf16 v[52:55], v[136:139], v[232:235], v[52:55]
	v_mfma_f32_16x16x32_bf16 v[48:51], v[164:167], v[232:235], v[48:51]
	v_mfma_f32_16x16x32_bf16 v[44:47], v[136:139], v[240:243], v[44:47]
	v_mfma_f32_16x16x32_bf16 v[40:43], v[164:167], v[240:243], v[40:43]
	v_mfma_f32_16x16x32_bf16 v[36:39], v[136:139], v[248:251], v[36:39]
	v_mfma_f32_16x16x32_bf16 v[32:35], v[164:167], v[248:251], v[32:35]
	s_setprio 0
	s_setprio 1
	v_mfma_f32_16x16x32_bf16 v[28:31], v[168:171], v[204:207], v[28:31]
	v_mfma_f32_16x16x32_bf16 v[24:27], v[216:219], v[204:207], v[24:27]
	v_mfma_f32_16x16x32_bf16 v[20:23], v[168:171], v[228:231], v[20:23]
	v_mfma_f32_16x16x32_bf16 v[16:19], v[216:219], v[228:231], v[16:19]
	v_mfma_f32_16x16x32_bf16 v[12:15], v[168:171], v[236:239], v[12:15]
	v_mfma_f32_16x16x32_bf16 v[8:11], v[216:219], v[236:239], v[8:11]
	v_mfma_f32_16x16x32_bf16 v[4:7], v[168:171], v[244:247], v[4:7]
	v_mfma_f32_16x16x32_bf16 v[0:3], v[216:219], v[244:247], v[0:3]
	s_setprio 0
	s_setprio 1
	v_mfma_f32_16x16x32_bf16 v[28:31], v[172:175], v[224:227], v[28:31]
	v_mfma_f32_16x16x32_bf16 v[24:27], v[220:223], v[224:227], v[24:27]
	v_mfma_f32_16x16x32_bf16 v[20:23], v[172:175], v[232:235], v[20:23]
	v_mfma_f32_16x16x32_bf16 v[16:19], v[220:223], v[232:235], v[16:19]
	v_mfma_f32_16x16x32_bf16 v[12:15], v[172:175], v[240:243], v[12:15]
	v_mfma_f32_16x16x32_bf16 v[8:11], v[220:223], v[240:243], v[8:11]
	v_mfma_f32_16x16x32_bf16 v[4:7], v[172:175], v[248:251], v[4:7]
	v_mfma_f32_16x16x32_bf16 v[0:3], v[220:223], v[248:251], v[0:3]
	s_setprio 0
	s_barrier
	s_add_i32 s22, 0, 0x18000
	v_add_u32_e32 v96, s22, v179
	s_add_i32 s23, 0, 0x1c000
	ds_read_b128 v[132:135], v96
	ds_read_b128 v[136:139], v96 offset:1024
	ds_read_b128 v[160:163], v96 offset:2048
	ds_read_b128 v[164:167], v96 offset:3072
	v_add_u32_e32 v96, s23, v179
	ds_read_b128 v[168:171], v96
	ds_read_b128 v[172:175], v96 offset:1024
	ds_read_b128 v[204:207], v96 offset:2048
	ds_read_b128 v[216:219], v96 offset:3072
	s_add_u32 s20, s20, s90
	s_addc_u32 s21, s21, s7
	s_mov_b32 m0, s73
	v_lshl_add_u64 v[102:103], s[20:21], 0, v[140:141]
	ds_read_b128 v[220:223], v188 offset:32768
	ds_read_b128 v[224:227], v188 offset:33792
	ds_read_b128 v[228:231], v188 offset:34816
	ds_read_b128 v[232:235], v188 offset:35840
	ds_read_b128 v[236:239], v188 offset:36864
	ds_read_b128 v[240:243], v188 offset:37888
	ds_read_b128 v[244:247], v188 offset:38912
	ds_read_b128 v[248:251], v188 offset:39936
	global_load_lds_dwordx4 v[102:103], off
	v_lshl_add_u64 v[102:103], s[20:21], 0, v[142:143]
	s_mov_b32 m0, s4
	s_nop 0
	global_load_lds_dwordx4 v[102:103], off
	s_waitcnt vmcnt(8)
	s_waitcnt lgkmcnt(0)
	s_barrier
	s_setprio 1
	s_waitcnt lgkmcnt(0)
	v_mfma_f32_16x16x32_bf16 v[128:131], v[132:135], v[220:223], v[128:131]
	v_mfma_f32_16x16x32_bf16 v[124:127], v[160:163], v[220:223], v[124:127]
	v_mfma_f32_16x16x32_bf16 v[120:123], v[132:135], v[228:231], v[120:123]
	v_mfma_f32_16x16x32_bf16 v[116:119], v[160:163], v[228:231], v[116:119]
	v_mfma_f32_16x16x32_bf16 v[112:115], v[132:135], v[236:239], v[112:115]
	v_mfma_f32_16x16x32_bf16 v[108:111], v[160:163], v[236:239], v[108:111]
	v_mfma_f32_16x16x32_bf16 v[102:105], v[132:135], v[244:247], v[104:107]
	v_mfma_f32_16x16x32_bf16 v[98:101], v[160:163], v[244:247], v[98:101]
	s_setprio 0
	s_setprio 1
	v_mfma_f32_16x16x32_bf16 v[128:131], v[136:139], v[224:227], v[128:131]
	v_mfma_f32_16x16x32_bf16 v[124:127], v[164:167], v[224:227], v[124:127]
	v_mfma_f32_16x16x32_bf16 v[120:123], v[136:139], v[232:235], v[120:123]
	v_mfma_f32_16x16x32_bf16 v[116:119], v[164:167], v[232:235], v[116:119]
	v_mfma_f32_16x16x32_bf16 v[112:115], v[136:139], v[240:243], v[112:115]
	v_mfma_f32_16x16x32_bf16 v[108:111], v[164:167], v[240:243], v[108:111]
	v_mfma_f32_16x16x32_bf16 v[104:107], v[136:139], v[248:251], v[102:105]
	v_mfma_f32_16x16x32_bf16 v[100:103], v[164:167], v[248:251], v[98:101]
	s_setprio 0
	s_setprio 1
	v_mfma_f32_16x16x32_bf16 v[92:95], v[168:171], v[220:223], v[92:95]
	v_mfma_f32_16x16x32_bf16 v[88:91], v[204:207], v[220:223], v[88:91]
	v_mfma_f32_16x16x32_bf16 v[84:87], v[168:171], v[228:231], v[84:87]
	v_mfma_f32_16x16x32_bf16 v[80:83], v[204:207], v[228:231], v[80:83]
	v_mfma_f32_16x16x32_bf16 v[76:79], v[168:171], v[236:239], v[76:79]
	v_mfma_f32_16x16x32_bf16 v[72:75], v[204:207], v[236:239], v[72:75]
	v_mfma_f32_16x16x32_bf16 v[68:71], v[168:171], v[244:247], v[68:71]
	v_mfma_f32_16x16x32_bf16 v[64:67], v[204:207], v[244:247], v[64:67]
	s_setprio 0
	s_setprio 1
	v_mfma_f32_16x16x32_bf16 v[92:95], v[172:175], v[224:227], v[92:95]
	v_mfma_f32_16x16x32_bf16 v[88:91], v[216:219], v[224:227], v[88:91]
	v_mfma_f32_16x16x32_bf16 v[84:87], v[172:175], v[232:235], v[84:87]
	v_mfma_f32_16x16x32_bf16 v[80:83], v[216:219], v[232:235], v[80:83]
	v_mfma_f32_16x16x32_bf16 v[76:79], v[172:175], v[240:243], v[76:79]
	v_mfma_f32_16x16x32_bf16 v[72:75], v[216:219], v[240:243], v[72:75]
	v_mfma_f32_16x16x32_bf16 v[68:71], v[172:175], v[248:251], v[68:71]
	v_mfma_f32_16x16x32_bf16 v[64:67], v[216:219], v[248:251], v[64:67]
	s_setprio 0
	s_barrier
; #define PG8_STAGE(bufoff, gbase, voff) do { _Pragma("unroll") for (int _i = 0; _i < 2; ++_i) \
;         __builtin_amdgcn_global_load_lds((const unsigned*)((const char*)(gbase) + (voff)[_i]), (LAS unsigned*)(lds + (bufoff) + ldsw + _i * 8192), 16, 0, 0); } while (0)
; #define PG8_LDA(dst, b, h) do { _Pragma("unroll") for (int m = 0; m < 4; ++m) _Pragma("unroll") for (int k = 0; k < 2; ++k) dst[m][k] = *(const LAS bf16x8*)(lds + PG8_SA(b, h) + aoff + m * 2048 + k * 1024); } while (0)
; #define PG8_LDB(dst, b, h) do { _Pragma("unroll") for (int n = 0; n < 2; ++n) _Pragma("unroll") for (int k = 0; k < 2; ++k) dst[n][k] = *(const LAS bf16x8*)(lds + PG8_SB(b, h) + boff + n * 2048 + k * 1024); } while (0)
; #define PG8_MMA(ai, bj, At, Bt) do { __builtin_amdgcn_s_setprio(1); _Pragma("unroll") for (int m = 0; m < 4; ++m) _Pragma("unroll") for (int n = 0; n < 2; ++n) _Pragma("unroll") for (int k = 0; k < 2; ++k) \
;         acc[ai][bj][m][n] = __builtin_amdgcn_mfma_f32_16x16x32_bf16(Bt[n][k], At[m][k], acc[ai][bj][m][n], 0, 0, 0); __builtin_amdgcn_s_setprio(0); } while (0)
; #define PG8_WAIT_V(n) asm volatile("s_waitcnt vmcnt(" #n ")" ::: "memory")
; #define PG8_WAIT_L(n) asm volatile("s_waitcnt lgkmcnt(" #n ")" ::: "memory")
; #define PG8_BAR __builtin_amdgcn_s_barrier()
; #define PG8_SCHED __builtin_amdgcn_sched_barrier(0)
; __device__ __forceinline__ void gemm_phase(LAS unsigned char* lds, const GemmP g, const EpiP e) {
;     ...
;         for (int t = 0; t < nt; t += 2) {
;             const bool last = (t == nt - 2);
;             const char* a1 = cA + (size_t)(t + 1) * kstepA;
;             const char* a2 = last ? nA : cA + (size_t)(t + 2) * kstepA; const char* b2 = last ? nB : cB + (size_t)(t + 2) * kstepB;
;             const char* a3 = a2 + kstepA; const char* b3 = b2 + kstepB;
;             PG8_LDB(B0, 0, 0); PG8_LDB(B1, 0, 1); PG8_SCHED; PG8_LDA(At, 0, 0); PG8_STAGE(PG8_SA(1, 1), a1 + hstepA, voffA);
;     ...
;             PG8_LDA(At, 1, 1); PG8_STAGE(PG8_SB(1, 0), b3, voffB); PG8_STAGE(PG8_SB(1, 1), b3 + hstepB, voffB); PG8_STAGE(PG8_SA(1, 0), a3, voffA);
;             PG8_WAIT_V(8); PG8_WAIT_L(0); PG8_BAR; PG8_MMA(1, 0, At, B0); PG8_MMA(1, 1, At, B1); PG8_BAR; PG8_SCHED;
;         }
	s_add_i32 s20, s22, s91
	v_lshl_add_u64 v[98:99], v[176:177], 0, s[96:97]
	s_mov_b32 m0, s20
	ds_read_b128 v[220:223], v188 offset:49152
	ds_read_b128 v[224:227], v188 offset:50176
	ds_read_b128 v[228:231], v188 offset:51200
	ds_read_b128 v[232:235], v188 offset:52224
	ds_read_b128 v[236:239], v188 offset:53248
	ds_read_b128 v[240:243], v188 offset:54272
	ds_read_b128 v[244:247], v188 offset:55296
	ds_read_b128 v[248:251], v188 offset:56320
	global_load_lds_dwordx4 v[98:99], off
	v_lshl_add_u64 v[98:99], v[210:211], 0, s[96:97]
	s_add_i32 m0, s20, 0x2000
	s_add_i32 s20, s23, s91
	global_load_lds_dwordx4 v[98:99], off
	v_lshl_add_u64 v[98:99], v[212:213], 0, s[96:97]
	s_mov_b32 m0, s20
	s_nop 0
	global_load_lds_dwordx4 v[98:99], off
	v_lshl_add_u64 v[98:99], v[190:191], 0, s[96:97]
	s_add_i32 m0, s20, 0x2000
	s_nop 0
	global_load_lds_dwordx4 v[98:99], off
	v_lshl_add_u64 v[98:99], s[18:19], 0, v[140:141]
	s_mov_b32 m0, s5
	s_nop 0
	global_load_lds_dwordx4 v[98:99], off
	v_lshl_add_u64 v[98:99], s[18:19], 0, v[142:143]
	s_mov_b32 m0, s44
	s_nop 0
	global_load_lds_dwordx4 v[98:99], off
	s_waitcnt vmcnt(8)
	s_waitcnt lgkmcnt(0)
	s_barrier
	s_setprio 1
	s_waitcnt lgkmcnt(0)
	v_mfma_f32_16x16x32_bf16 v[60:63], v[132:135], v[220:223], v[60:63]
	v_mfma_f32_16x16x32_bf16 v[56:59], v[160:163], v[220:223], v[56:59]
	v_mfma_f32_16x16x32_bf16 v[52:55], v[132:135], v[228:231], v[52:55]
	v_mfma_f32_16x16x32_bf16 v[48:51], v[160:163], v[228:231], v[48:51]
	v_mfma_f32_16x16x32_bf16 v[44:47], v[132:135], v[236:239], v[44:47]
	v_mfma_f32_16x16x32_bf16 v[40:43], v[160:163], v[236:239], v[40:43]
	v_mfma_f32_16x16x32_bf16 v[36:39], v[132:135], v[244:247], v[36:39]
	v_mfma_f32_16x16x32_bf16 v[32:35], v[160:163], v[244:247], v[32:35]
	s_setprio 0
	s_setprio 1
	v_mfma_f32_16x16x32_bf16 v[60:63], v[136:139], v[224:227], v[60:63]
	v_mfma_f32_16x16x32_bf16 v[56:59], v[164:167], v[224:227], v[56:59]
	v_mfma_f32_16x16x32_bf16 v[52:55], v[136:139], v[232:235], v[52:55]
	v_mfma_f32_16x16x32_bf16 v[48:51], v[164:167], v[232:235], v[48:51]
	v_mfma_f32_16x16x32_bf16 v[44:47], v[136:139], v[240:243], v[44:47]
	v_mfma_f32_16x16x32_bf16 v[40:43], v[164:167], v[240:243], v[40:43]
	v_mfma_f32_16x16x32_bf16 v[36:39], v[136:139], v[248:251], v[36:39]
	v_mfma_f32_16x16x32_bf16 v[32:35], v[164:167], v[248:251], v[32:35]
	s_setprio 0
	s_setprio 1
	v_mfma_f32_16x16x32_bf16 v[28:31], v[168:171], v[220:223], v[28:31]
	v_mfma_f32_16x16x32_bf16 v[24:27], v[204:207], v[220:223], v[24:27]
	v_mfma_f32_16x16x32_bf16 v[20:23], v[168:171], v[228:231], v[20:23]
	v_mfma_f32_16x16x32_bf16 v[16:19], v[204:207], v[228:231], v[16:19]
	v_mfma_f32_16x16x32_bf16 v[12:15], v[168:171], v[236:239], v[12:15]
	v_mfma_f32_16x16x32_bf16 v[8:11], v[204:207], v[236:239], v[8:11]
	v_mfma_f32_16x16x32_bf16 v[4:7], v[168:171], v[244:247], v[4:7]
	v_mfma_f32_16x16x32_bf16 v[0:3], v[204:207], v[244:247], v[0:3]
	s_setprio 0
	s_setprio 1
	v_mfma_f32_16x16x32_bf16 v[28:31], v[172:175], v[224:227], v[28:31]
	v_mfma_f32_16x16x32_bf16 v[24:27], v[216:219], v[224:227], v[24:27]
	v_mfma_f32_16x16x32_bf16 v[20:23], v[172:175], v[232:235], v[20:23]
	v_mfma_f32_16x16x32_bf16 v[16:19], v[216:219], v[232:235], v[16:19]
	v_mfma_f32_16x16x32_bf16 v[12:15], v[172:175], v[240:243], v[12:15]
	v_mfma_f32_16x16x32_bf16 v[8:11], v[216:219], v[240:243], v[8:11]
	v_mfma_f32_16x16x32_bf16 v[4:7], v[172:175], v[248:251], v[4:7]
	v_mfma_f32_16x16x32_bf16 v[0:3], v[216:219], v[248:251], v[0:3]
	s_setprio 0
	s_barrier
	s_add_u32 s27, s27, 0x100
	s_addc_u32 s28, s28, 0
	s_cmp_ge_i32 s16, s69
	s_mov_b64 s[18:19], s[16:17]
	s_cbranch_scc0 .LBB0_394
	s_branch .LBB0_395
	.p2align 6
	s_nop 0
	s_nop 0
	s_nop 0
	s_nop 0
	s_nop 0
	s_nop 0
	s_nop 0
	s_nop 0
.LBB0_394:
	s_add_u32 s30, s18, 1
	s_addc_u32 s31, s19, 0
	s_add_u32 s16, s18, 2
	s_addc_u32 s17, s19, 0
	s_lshl_b64 s[20:21], s[16:17], s77
	s_add_u32 s19, s78, s20
	s_addc_u32 s20, s79, s21
	s_cmp_eq_u32 s26, s18
	s_cselect_b32 s21, s51, s20
	s_cselect_b32 s20, s50, s19
	s_cselect_b32 s22, s80, s27
	s_cselect_b32 s23, s81, s28
	s_add_u32 s18, s20, s38
	s_addc_u32 s19, s21, s39
	s_add_i32 s29, 0, 0x10000
	v_add_u32_e32 v96, s29, v179
	s_add_i32 s34, 0, 0x14000
	ds_read_b128 v[132:135], v96
	ds_read_b128 v[136:139], v96 offset:1024
	ds_read_b128 v[160:163], v96 offset:2048
	ds_read_b128 v[164:167], v96 offset:3072
	v_add_u32_e32 v96, s34, v179
	ds_read_b128 v[168:171], v96
	ds_read_b128 v[172:175], v96 offset:1024
	ds_read_b128 v[216:219], v96 offset:2048
	ds_read_b128 v[220:223], v96 offset:3072
	s_lshl_b64 s[30:31], s[30:31], s77
	s_add_u32 s30, s24, s30
	s_addc_u32 s31, s25, s31
	v_lshl_add_u64 v[98:99], s[30:31], 0, v[140:141]
	s_add_i32 m0, s92, 0xc000
	ds_read_b128 v[224:227], v188
	ds_read_b128 v[228:231], v188 offset:1024
	ds_read_b128 v[232:235], v188 offset:2048
	ds_read_b128 v[236:239], v188 offset:3072
	ds_read_b128 v[240:243], v188 offset:4096
	ds_read_b128 v[244:247], v188 offset:5120
	ds_read_b128 v[248:251], v188 offset:6144
	ds_read_b128 v[204:207], v188 offset:7168
	global_load_lds_dwordx4 v[98:99], off
	v_lshl_add_u64 v[98:99], s[30:31], 0, v[142:143]
	s_add_i32 m0, s92, 0xe000
	s_nop 0
	global_load_lds_dwordx4 v[98:99], off
	s_waitcnt vmcnt(8)
	s_waitcnt lgkmcnt(0)
	s_barrier
; #define PG8_STAGE(bufoff, gbase, voff) do { _Pragma("unroll") for (int _i = 0; _i < 2; ++_i) \
;         __builtin_amdgcn_global_load_lds((const unsigned*)((const char*)(gbase) + (voff)[_i]), (LAS unsigned*)(lds + (bufoff) + ldsw + _i * 8192), 16, 0, 0); } while (0)
; #define PG8_LDA(dst, b, h) do { _Pragma("unroll") for (int m = 0; m < 4; ++m) _Pragma("unroll") for (int k = 0; k < 2; ++k) dst[m][k] = *(const LAS bf16x8*)(lds + PG8_SA(b, h) + aoff + m * 2048 + k * 1024); } while (0)
; #define PG8_LDB(dst, b, h) do { _Pragma("unroll") for (int n = 0; n < 2; ++n) _Pragma("unroll") for (int k = 0; k < 2; ++k) dst[n][k] = *(const LAS bf16x8*)(lds + PG8_SB(b, h) + boff + n * 2048 + k * 1024); } while (0)
; #define PG8_MMA(ai, bj, At, Bt) do { __builtin_amdgcn_s_setprio(1); _Pragma("unroll") for (int m = 0; m < 4; ++m) _Pragma("unroll") for (int n = 0; n < 2; ++n) _Pragma("unroll") for (int k = 0; k < 2; ++k) \
;         acc[ai][bj][m][n] = __builtin_amdgcn_mfma_f32_16x16x32_bf16(Bt[n][k], At[m][k], acc[ai][bj][m][n], 0, 0, 0); __builtin_amdgcn_s_setprio(0); } while (0)
; #define PG8_WAIT_V(n) asm volatile("s_waitcnt vmcnt(" #n ")" ::: "memory")
; #define PG8_WAIT_L(n) asm volatile("s_waitcnt lgkmcnt(" #n ")" ::: "memory")
; #define PG8_BAR __builtin_amdgcn_s_barrier()
; #define PG8_SCHED __builtin_amdgcn_sched_barrier(0)
; __device__ __forceinline__ void gemm_phase(LAS unsigned char* lds, const GemmP g, const EpiP e) {
;     ...
;             PG8_LDB(B0, 0, 0); PG8_LDB(B1, 0, 1); PG8_SCHED; PG8_LDA(At, 0, 0); PG8_STAGE(PG8_SA(1, 1), a1 + hstepA, voffA);
;             PG8_WAIT_V(8); PG8_WAIT_L(0); PG8_BAR; PG8_MMA(0, 0, At, B0); PG8_MMA(0, 1, At, B1); PG8_BAR; PG8_SCHED;
;             PG8_LDA(At, 0, 1); PG8_STAGE(PG8_SB(0, 0), b2, voffB); PG8_STAGE(PG8_SB(0, 1), b2 + hstepB, voffB); PG8_STAGE(PG8_SA(0, 0), a2, voffA);
;             PG8_WAIT_V(8); PG8_WAIT_L(0); PG8_BAR; PG8_MMA(1, 0, At, B0); PG8_MMA(1, 1, At, B1); PG8_BAR; PG8_SCHED;
	s_setprio 1
	s_waitcnt lgkmcnt(0)
	v_mfma_f32_16x16x32_bf16 v[128:131], v[132:135], v[224:227], v[128:131]
	v_mfma_f32_16x16x32_bf16 v[124:127], v[160:163], v[224:227], v[124:127]
	v_mfma_f32_16x16x32_bf16 v[120:123], v[132:135], v[232:235], v[120:123]
	v_mfma_f32_16x16x32_bf16 v[116:119], v[160:163], v[232:235], v[116:119]
	v_mfma_f32_16x16x32_bf16 v[112:115], v[132:135], v[240:243], v[112:115]
	v_mfma_f32_16x16x32_bf16 v[108:111], v[160:163], v[240:243], v[108:111]
	v_mfma_f32_16x16x32_bf16 v[104:107], v[132:135], v[248:251], v[104:107]
	v_mfma_f32_16x16x32_bf16 v[98:101], v[160:163], v[248:251], v[100:103]
	s_setprio 0
	s_setprio 1
	v_mfma_f32_16x16x32_bf16 v[128:131], v[136:139], v[228:231], v[128:131]
	v_mfma_f32_16x16x32_bf16 v[124:127], v[164:167], v[228:231], v[124:127]
	v_mfma_f32_16x16x32_bf16 v[120:123], v[136:139], v[236:239], v[120:123]
	v_mfma_f32_16x16x32_bf16 v[116:119], v[164:167], v[236:239], v[116:119]
	v_mfma_f32_16x16x32_bf16 v[112:115], v[136:139], v[244:247], v[112:115]
	v_mfma_f32_16x16x32_bf16 v[108:111], v[164:167], v[244:247], v[108:111]
	v_mfma_f32_16x16x32_bf16 v[104:107], v[136:139], v[204:207], v[104:107]
	v_mfma_f32_16x16x32_bf16 v[98:101], v[164:167], v[204:207], v[98:101]
	s_setprio 0
	s_setprio 1
	v_mfma_f32_16x16x32_bf16 v[92:95], v[168:171], v[224:227], v[92:95]
	v_mfma_f32_16x16x32_bf16 v[88:91], v[216:219], v[224:227], v[88:91]
	v_mfma_f32_16x16x32_bf16 v[84:87], v[168:171], v[232:235], v[84:87]
	v_mfma_f32_16x16x32_bf16 v[80:83], v[216:219], v[232:235], v[80:83]
	v_mfma_f32_16x16x32_bf16 v[76:79], v[168:171], v[240:243], v[76:79]
	v_mfma_f32_16x16x32_bf16 v[72:75], v[216:219], v[240:243], v[72:75]
	v_mfma_f32_16x16x32_bf16 v[68:71], v[168:171], v[248:251], v[68:71]
	v_mfma_f32_16x16x32_bf16 v[64:67], v[216:219], v[248:251], v[64:67]
	s_setprio 0
	s_setprio 1
	v_mfma_f32_16x16x32_bf16 v[92:95], v[172:175], v[228:231], v[92:95]
	v_mfma_f32_16x16x32_bf16 v[88:91], v[220:223], v[228:231], v[88:91]
	v_mfma_f32_16x16x32_bf16 v[84:87], v[172:175], v[236:239], v[84:87]
	v_mfma_f32_16x16x32_bf16 v[80:83], v[220:223], v[236:239], v[80:83]
	v_mfma_f32_16x16x32_bf16 v[76:79], v[172:175], v[244:247], v[76:79]
	v_mfma_f32_16x16x32_bf16 v[72:75], v[220:223], v[244:247], v[72:75]
	v_mfma_f32_16x16x32_bf16 v[68:71], v[172:175], v[204:207], v[68:71]
	v_mfma_f32_16x16x32_bf16 v[64:67], v[220:223], v[204:207], v[64:67]
	s_setprio 0
	s_barrier
	s_add_i32 s29, s29, s91
	v_lshl_add_u64 v[176:177], s[22:23], 0, v[146:147]
	s_mov_b32 m0, s29
	ds_read_b128 v[204:207], v188 offset:16384
	ds_read_b128 v[224:227], v188 offset:17408
	ds_read_b128 v[228:231], v188 offset:18432
	ds_read_b128 v[232:235], v188 offset:19456
	ds_read_b128 v[236:239], v188 offset:20480
	ds_read_b128 v[240:243], v188 offset:21504
	ds_read_b128 v[244:247], v188 offset:22528
	ds_read_b128 v[248:251], v188 offset:23552
	global_load_lds_dwordx4 v[176:177], off
	s_add_i32 m0, s29, 0x2000
	v_lshl_add_u64 v[210:211], s[22:23], 0, v[144:145]
	s_add_u32 s22, s22, s48
	s_addc_u32 s23, s23, s49
	s_add_i32 s29, s34, s91
	global_load_lds_dwordx4 v[210:211], off
	v_lshl_add_u64 v[212:213], s[22:23], 0, v[146:147]
	s_mov_b32 m0, s29
	v_lshl_add_u64 v[190:191], s[22:23], 0, v[144:145]
	global_load_lds_dwordx4 v[212:213], off
	s_add_i32 m0, s29, 0x2000
	v_lshl_add_u64 v[102:103], s[20:21], 0, v[140:141]
	global_load_lds_dwordx4 v[190:191], off
	s_mov_b32 m0, s92
	s_nop 0
	global_load_lds_dwordx4 v[102:103], off
	v_lshl_add_u64 v[102:103], s[20:21], 0, v[142:143]
	s_mov_b32 m0, s93
	s_nop 0
	global_load_lds_dwordx4 v[102:103], off
	s_waitcnt vmcnt(8)
	s_waitcnt lgkmcnt(0)
	s_barrier
	s_setprio 1
	s_waitcnt lgkmcnt(0)
	v_mfma_f32_16x16x32_bf16 v[60:63], v[132:135], v[204:207], v[60:63]
	v_mfma_f32_16x16x32_bf16 v[56:59], v[160:163], v[204:207], v[56:59]
	v_mfma_f32_16x16x32_bf16 v[52:55], v[132:135], v[228:231], v[52:55]
	v_mfma_f32_16x16x32_bf16 v[48:51], v[160:163], v[228:231], v[48:51]
	v_mfma_f32_16x16x32_bf16 v[44:47], v[132:135], v[236:239], v[44:47]
	v_mfma_f32_16x16x32_bf16 v[40:43], v[160:163], v[236:239], v[40:43]
	v_mfma_f32_16x16x32_bf16 v[36:39], v[132:135], v[244:247], v[36:39]
	v_mfma_f32_16x16x32_bf16 v[32:35], v[160:163], v[244:247], v[32:35]
	s_setprio 0
	s_setprio 1
	v_mfma_f32_16x16x32_bf16 v[60:63], v[136:139], v[224:227], v[60:63]
	v_mfma_f32_16x16x32_bf16 v[56:59], v[164:167], v[224:227], v[56:59]
	v_mfma_f32_16x16x32_bf16 v[52:55], v[136:139], v[232:235], v[52:55]
	v_mfma_f32_16x16x32_bf16 v[48:51], v[164:167], v[232:235], v[48:51]
	v_mfma_f32_16x16x32_bf16 v[44:47], v[136:139], v[240:243], v[44:47]
	v_mfma_f32_16x16x32_bf16 v[40:43], v[164:167], v[240:243], v[40:43]
	v_mfma_f32_16x16x32_bf16 v[36:39], v[136:139], v[248:251], v[36:39]
	v_mfma_f32_16x16x32_bf16 v[32:35], v[164:167], v[248:251], v[32:35]
	s_setprio 0
	s_setprio 1
	v_mfma_f32_16x16x32_bf16 v[28:31], v[168:171], v[204:207], v[28:31]
	v_mfma_f32_16x16x32_bf16 v[24:27], v[216:219], v[204:207], v[24:27]
	v_mfma_f32_16x16x32_bf16 v[20:23], v[168:171], v[228:231], v[20:23]
	v_mfma_f32_16x16x32_bf16 v[16:19], v[216:219], v[228:231], v[16:19]
	v_mfma_f32_16x16x32_bf16 v[12:15], v[168:171], v[236:239], v[12:15]
	v_mfma_f32_16x16x32_bf16 v[8:11], v[216:219], v[236:239], v[8:11]
	v_mfma_f32_16x16x32_bf16 v[4:7], v[168:171], v[244:247], v[4:7]
	v_mfma_f32_16x16x32_bf16 v[0:3], v[216:219], v[244:247], v[0:3]
	s_setprio 0
	s_setprio 1
	v_mfma_f32_16x16x32_bf16 v[28:31], v[172:175], v[224:227], v[28:31]
	v_mfma_f32_16x16x32_bf16 v[24:27], v[220:223], v[224:227], v[24:27]
	v_mfma_f32_16x16x32_bf16 v[20:23], v[172:175], v[232:235], v[20:23]
	v_mfma_f32_16x16x32_bf16 v[16:19], v[220:223], v[232:235], v[16:19]
	v_mfma_f32_16x16x32_bf16 v[12:15], v[172:175], v[240:243], v[12:15]
	v_mfma_f32_16x16x32_bf16 v[8:11], v[220:223], v[240:243], v[8:11]
	v_mfma_f32_16x16x32_bf16 v[4:7], v[172:175], v[248:251], v[4:7]
	v_mfma_f32_16x16x32_bf16 v[0:3], v[220:223], v[248:251], v[0:3]
	s_setprio 0
	s_barrier
; #define PG8_STAGE(bufoff, gbase, voff) do { _Pragma("unroll") for (int _i = 0; _i < 2; ++_i) \
;         __builtin_amdgcn_global_load_lds((const unsigned*)((const char*)(gbase) + (voff)[_i]), (LAS unsigned*)(lds + (bufoff) + ldsw + _i * 8192), 16, 0, 0); } while (0)
; #define PG8_LDA(dst, b, h) do { _Pragma("unroll") for (int m = 0; m < 4; ++m) _Pragma("unroll") for (int k = 0; k < 2; ++k) dst[m][k] = *(const LAS bf16x8*)(lds + PG8_SA(b, h) + aoff + m * 2048 + k * 1024); } while (0)
; #define PG8_LDB(dst, b, h) do { _Pragma("unroll") for (int n = 0; n < 2; ++n) _Pragma("unroll") for (int k = 0; k < 2; ++k) dst[n][k] = *(const LAS bf16x8*)(lds + PG8_SB(b, h) + boff + n * 2048 + k * 1024); } while (0)
; #define PG8_MMA(ai, bj, At, Bt) do { __builtin_amdgcn_s_setprio(1); _Pragma("unroll") for (int m = 0; m < 4; ++m) _Pragma("unroll") for (int n = 0; n < 2; ++n) _Pragma("unroll") for (int k = 0; k < 2; ++k) \
;         acc[ai][bj][m][n] = __builtin_amdgcn_mfma_f32_16x16x32_bf16(Bt[n][k], At[m][k], acc[ai][bj][m][n], 0, 0, 0); __builtin_amdgcn_s_setprio(0); } while (0)
; #define PG8_WAIT_V(n) asm volatile("s_waitcnt vmcnt(" #n ")" ::: "memory")
; #define PG8_WAIT_L(n) asm volatile("s_waitcnt lgkmcnt(" #n ")" ::: "memory")
; #define PG8_BAR __builtin_amdgcn_s_barrier()
; #define PG8_SCHED __builtin_amdgcn_sched_barrier(0)
; __device__ __forceinline__ void gemm_phase(LAS unsigned char* lds, const GemmP g, const EpiP e) {
;     ...
;             PG8_LDB(B0, 1, 0); PG8_LDB(B1, 1, 1); PG8_SCHED; PG8_LDA(At, 1, 0); PG8_STAGE(PG8_SA(0, 1), a2 + hstepA, voffA);
;             PG8_WAIT_V(8); PG8_WAIT_L(0); PG8_BAR; PG8_MMA(0, 0, At, B0); PG8_MMA(0, 1, At, B1); PG8_BAR; PG8_SCHED;
;             PG8_LDA(At, 1, 1); PG8_STAGE(PG8_SB(1, 0), b3, voffB); PG8_STAGE(PG8_SB(1, 1), b3 + hstepB, voffB); PG8_STAGE(PG8_SA(1, 0), a3, voffA);
	s_add_i32 s22, 0, 0x18000
	v_add_u32_e32 v96, s22, v179
	s_add_i32 s23, 0, 0x1c000
	ds_read_b128 v[132:135], v96
	ds_read_b128 v[136:139], v96 offset:1024
	ds_read_b128 v[160:163], v96 offset:2048
	ds_read_b128 v[164:167], v96 offset:3072
	v_add_u32_e32 v96, s23, v179
	ds_read_b128 v[168:171], v96
	ds_read_b128 v[172:175], v96 offset:1024
	ds_read_b128 v[204:207], v96 offset:2048
	ds_read_b128 v[216:219], v96 offset:3072
	s_add_u32 s20, s20, s90
	s_addc_u32 s21, s21, s7
	s_mov_b32 m0, s73
	v_lshl_add_u64 v[102:103], s[20:21], 0, v[140:141]
	ds_read_b128 v[220:223], v188 offset:32768
	ds_read_b128 v[224:227], v188 offset:33792
	ds_read_b128 v[228:231], v188 offset:34816
	ds_read_b128 v[232:235], v188 offset:35840
	ds_read_b128 v[236:239], v188 offset:36864
	ds_read_b128 v[240:243], v188 offset:37888
	ds_read_b128 v[244:247], v188 offset:38912
	ds_read_b128 v[248:251], v188 offset:39936
	global_load_lds_dwordx4 v[102:103], off
	v_lshl_add_u64 v[102:103], s[20:21], 0, v[142:143]
	s_mov_b32 m0, s4
	s_nop 0
	global_load_lds_dwordx4 v[102:103], off
	s_waitcnt vmcnt(8)
	s_waitcnt lgkmcnt(0)
	s_barrier
	s_setprio 1
	s_waitcnt lgkmcnt(0)
	v_mfma_f32_16x16x32_bf16 v[128:131], v[132:135], v[220:223], v[128:131]
	v_mfma_f32_16x16x32_bf16 v[124:127], v[160:163], v[220:223], v[124:127]
	v_mfma_f32_16x16x32_bf16 v[120:123], v[132:135], v[228:231], v[120:123]
	v_mfma_f32_16x16x32_bf16 v[116:119], v[160:163], v[228:231], v[116:119]
	v_mfma_f32_16x16x32_bf16 v[112:115], v[132:135], v[236:239], v[112:115]
	v_mfma_f32_16x16x32_bf16 v[108:111], v[160:163], v[236:239], v[108:111]
	v_mfma_f32_16x16x32_bf16 v[102:105], v[132:135], v[244:247], v[104:107]
	v_mfma_f32_16x16x32_bf16 v[98:101], v[160:163], v[244:247], v[98:101]
	s_setprio 0
	s_setprio 1
	v_mfma_f32_16x16x32_bf16 v[128:131], v[136:139], v[224:227], v[128:131]
	v_mfma_f32_16x16x32_bf16 v[124:127], v[164:167], v[224:227], v[124:127]
	v_mfma_f32_16x16x32_bf16 v[120:123], v[136:139], v[232:235], v[120:123]
	v_mfma_f32_16x16x32_bf16 v[116:119], v[164:167], v[232:235], v[116:119]
	v_mfma_f32_16x16x32_bf16 v[112:115], v[136:139], v[240:243], v[112:115]
	v_mfma_f32_16x16x32_bf16 v[108:111], v[164:167], v[240:243], v[108:111]
	v_mfma_f32_16x16x32_bf16 v[104:107], v[136:139], v[248:251], v[102:105]
	v_mfma_f32_16x16x32_bf16 v[100:103], v[164:167], v[248:251], v[98:101]
	s_setprio 0
	s_setprio 1
	v_mfma_f32_16x16x32_bf16 v[92:95], v[168:171], v[220:223], v[92:95]
	v_mfma_f32_16x16x32_bf16 v[88:91], v[204:207], v[220:223], v[88:91]
	v_mfma_f32_16x16x32_bf16 v[84:87], v[168:171], v[228:231], v[84:87]
	v_mfma_f32_16x16x32_bf16 v[80:83], v[204:207], v[228:231], v[80:83]
	v_mfma_f32_16x16x32_bf16 v[76:79], v[168:171], v[236:239], v[76:79]
	v_mfma_f32_16x16x32_bf16 v[72:75], v[204:207], v[236:239], v[72:75]
	v_mfma_f32_16x16x32_bf16 v[68:71], v[168:171], v[244:247], v[68:71]
	v_mfma_f32_16x16x32_bf16 v[64:67], v[204:207], v[244:247], v[64:67]
	s_setprio 0
	s_setprio 1
	v_mfma_f32_16x16x32_bf16 v[92:95], v[172:175], v[224:227], v[92:95]
	v_mfma_f32_16x16x32_bf16 v[88:91], v[216:219], v[224:227], v[88:91]
	v_mfma_f32_16x16x32_bf16 v[84:87], v[172:175], v[232:235], v[84:87]
	v_mfma_f32_16x16x32_bf16 v[80:83], v[216:219], v[232:235], v[80:83]
	v_mfma_f32_16x16x32_bf16 v[76:79], v[172:175], v[240:243], v[76:79]
	v_mfma_f32_16x16x32_bf16 v[72:75], v[216:219], v[240:243], v[72:75]
	v_mfma_f32_16x16x32_bf16 v[68:71], v[172:175], v[248:251], v[68:71]
	v_mfma_f32_16x16x32_bf16 v[64:67], v[216:219], v[248:251], v[64:67]
	s_setprio 0
	s_barrier
; #define PG8_STAGE(bufoff, gbase, voff) do { _Pragma("unroll") for (int _i = 0; _i < 2; ++_i) \
;         __builtin_amdgcn_global_load_lds((const unsigned*)((const char*)(gbase) + (voff)[_i]), (LAS unsigned*)(lds + (bufoff) + ldsw + _i * 8192), 16, 0, 0); } while (0)
; #define PG8_LDA(dst, b, h) do { _Pragma("unroll") for (int m = 0; m < 4; ++m) _Pragma("unroll") for (int k = 0; k < 2; ++k) dst[m][k] = *(const LAS bf16x8*)(lds + PG8_SA(b, h) + aoff + m * 2048 + k * 1024); } while (0)
; #define PG8_MMA(ai, bj, At, Bt) do { __builtin_amdgcn_s_setprio(1); _Pragma("unroll") for (int m = 0; m < 4; ++m) _Pragma("unroll") for (int n = 0; n < 2; ++n) _Pragma("unroll") for (int k = 0; k < 2; ++k) \
;         acc[ai][bj][m][n] = __builtin_amdgcn_mfma_f32_16x16x32_bf16(Bt[n][k], At[m][k], acc[ai][bj][m][n], 0, 0, 0); __builtin_amdgcn_s_setprio(0); } while (0)
; #define PG8_WAIT_V(n) asm volatile("s_waitcnt vmcnt(" #n ")" ::: "memory")
; #define PG8_WAIT_L(n) asm volatile("s_waitcnt lgkmcnt(" #n ")" ::: "memory")
; #define PG8_BAR __builtin_amdgcn_s_barrier()
; #define PG8_SCHED __builtin_amdgcn_sched_barrier(0)
; __device__ __forceinline__ void gemm_phase(LAS unsigned char* lds, const GemmP g, const EpiP e) {
;     ...
;             PG8_LDA(At, 1, 1); PG8_STAGE(PG8_SB(1, 0), b3, voffB); PG8_STAGE(PG8_SB(1, 1), b3 + hstepB, voffB); PG8_STAGE(PG8_SA(1, 0), a3, voffA);
;             PG8_WAIT_V(8); PG8_WAIT_L(0); PG8_BAR; PG8_MMA(1, 0, At, B0); PG8_MMA(1, 1, At, B1); PG8_BAR; PG8_SCHED;
	s_add_i32 s20, s22, s91
	v_lshl_add_u64 v[98:99], v[176:177], 0, s[96:97]
	s_mov_b32 m0, s20
	ds_read_b128 v[220:223], v188 offset:49152
	ds_read_b128 v[224:227], v188 offset:50176
	ds_read_b128 v[228:231], v188 offset:51200
	ds_read_b128 v[232:235], v188 offset:52224
	ds_read_b128 v[236:239], v188 offset:53248
	ds_read_b128 v[240:243], v188 offset:54272
	ds_read_b128 v[244:247], v188 offset:55296
	ds_read_b128 v[248:251], v188 offset:56320
	global_load_lds_dwordx4 v[98:99], off
	v_lshl_add_u64 v[98:99], v[210:211], 0, s[96:97]
	s_add_i32 m0, s20, 0x2000
	s_add_i32 s20, s23, s91
	global_load_lds_dwordx4 v[98:99], off
	v_lshl_add_u64 v[98:99], v[212:213], 0, s[96:97]
	s_mov_b32 m0, s20
	s_nop 0
	global_load_lds_dwordx4 v[98:99], off
	v_lshl_add_u64 v[98:99], v[190:191], 0, s[96:97]
	s_add_i32 m0, s20, 0x2000
	s_nop 0
	global_load_lds_dwordx4 v[98:99], off
	v_lshl_add_u64 v[98:99], s[18:19], 0, v[140:141]
	s_mov_b32 m0, s5
	s_nop 0
	global_load_lds_dwordx4 v[98:99], off
	v_lshl_add_u64 v[98:99], s[18:19], 0, v[142:143]
	s_mov_b32 m0, s44
	s_nop 0
	global_load_lds_dwordx4 v[98:99], off
	s_waitcnt vmcnt(8)
	s_waitcnt lgkmcnt(0)
	s_barrier
	s_setprio 1
	s_waitcnt lgkmcnt(0)
	v_mfma_f32_16x16x32_bf16 v[60:63], v[132:135], v[220:223], v[60:63]
	v_mfma_f32_16x16x32_bf16 v[56:59], v[160:163], v[220:223], v[56:59]
	v_mfma_f32_16x16x32_bf16 v[52:55], v[132:135], v[228:231], v[52:55]
	v_mfma_f32_16x16x32_bf16 v[48:51], v[160:163], v[228:231], v[48:51]
	v_mfma_f32_16x16x32_bf16 v[44:47], v[132:135], v[236:239], v[44:47]
	v_mfma_f32_16x16x32_bf16 v[40:43], v[160:163], v[236:239], v[40:43]
	v_mfma_f32_16x16x32_bf16 v[36:39], v[132:135], v[244:247], v[36:39]
	v_mfma_f32_16x16x32_bf16 v[32:35], v[160:163], v[244:247], v[32:35]
	s_setprio 0
	s_setprio 1
	v_mfma_f32_16x16x32_bf16 v[60:63], v[136:139], v[224:227], v[60:63]
	v_mfma_f32_16x16x32_bf16 v[56:59], v[164:167], v[224:227], v[56:59]
	v_mfma_f32_16x16x32_bf16 v[52:55], v[136:139], v[232:235], v[52:55]
	v_mfma_f32_16x16x32_bf16 v[48:51], v[164:167], v[232:235], v[48:51]
	v_mfma_f32_16x16x32_bf16 v[44:47], v[136:139], v[240:243], v[44:47]
	v_mfma_f32_16x16x32_bf16 v[40:43], v[164:167], v[240:243], v[40:43]
	v_mfma_f32_16x16x32_bf16 v[36:39], v[136:139], v[248:251], v[36:39]
	v_mfma_f32_16x16x32_bf16 v[32:35], v[164:167], v[248:251], v[32:35]
	s_setprio 0
	s_setprio 1
	v_mfma_f32_16x16x32_bf16 v[28:31], v[168:171], v[220:223], v[28:31]
	v_mfma_f32_16x16x32_bf16 v[24:27], v[204:207], v[220:223], v[24:27]
	v_mfma_f32_16x16x32_bf16 v[20:23], v[168:171], v[228:231], v[20:23]
	v_mfma_f32_16x16x32_bf16 v[16:19], v[204:207], v[228:231], v[16:19]
	v_mfma_f32_16x16x32_bf16 v[12:15], v[168:171], v[236:239], v[12:15]
	v_mfma_f32_16x16x32_bf16 v[8:11], v[204:207], v[236:239], v[8:11]
	v_mfma_f32_16x16x32_bf16 v[4:7], v[168:171], v[244:247], v[4:7]
	v_mfma_f32_16x16x32_bf16 v[0:3], v[204:207], v[244:247], v[0:3]
	s_setprio 0
	s_setprio 1
	v_mfma_f32_16x16x32_bf16 v[28:31], v[172:175], v[224:227], v[28:31]
	v_mfma_f32_16x16x32_bf16 v[24:27], v[216:219], v[224:227], v[24:27]
	v_mfma_f32_16x16x32_bf16 v[20:23], v[172:175], v[232:235], v[20:23]
	v_mfma_f32_16x16x32_bf16 v[16:19], v[216:219], v[232:235], v[16:19]
	v_mfma_f32_16x16x32_bf16 v[12:15], v[172:175], v[240:243], v[12:15]
	v_mfma_f32_16x16x32_bf16 v[8:11], v[216:219], v[240:243], v[8:11]
	v_mfma_f32_16x16x32_bf16 v[4:7], v[172:175], v[248:251], v[4:7]
	v_mfma_f32_16x16x32_bf16 v[0:3], v[216:219], v[248:251], v[0:3]
	s_setprio 0
	s_barrier
	s_add_u32 s27, s27, 0x100
	s_addc_u32 s28, s28, 0
	s_cmp_ge_i32 s16, s69
	s_mov_b64 s[18:19], s[16:17]
	s_cbranch_scc0 .LBB0_394
